# v55 + P6: waves 4-7 sleep 704 cycles at each tile start (stagger MFMA and exp sections of the two waves per SIMD)
# speedup vs baseline: 1.0003x; 1.0003x over previous
.LBB0_721:
	v_readlane_b32 s32, v235, 17
	s_cmp_lt_u32 s32, 4
	s_cbranch_scc1 .Lp6stg
	s_sleep 11
